# g2_loader_prefetch_depth_4
# baseline (speedup 1.0000x reference)
.Lg2l_nocd_1:
	s_or_b64 exec, exec, s[8:9]
	global_load_dwordx4 v[0:3], v120, s[44:45]
	global_load_dwordx4 v[4:7], v120, s[46:47]
	global_load_dwordx4 v[8:11], v120, s[48:49]
	global_load_dwordx4 v[12:15], v120, s[50:51]
	global_load_dwordx4 v[16:19], v120, s[52:53]
	global_load_dwordx4 v[20:23], v120, s[54:55]
	global_load_dwordx4 v[24:27], v120, s[56:57]
	global_load_dwordx4 v[28:31], v120, s[58:59]
	global_load_dwordx4 v[32:35], v120, s[60:61]
	global_load_dwordx4 v[36:39], v120, s[62:63]
	global_load_dword v127, v121, s[72:73]
	s_add_u32 s44, s44, 0x18000
	s_addc_u32 s45, s45, 0
	s_add_u32 s46, s46, 0x18000
	s_addc_u32 s47, s47, 0
	s_add_u32 s48, s48, 0x18000
	s_addc_u32 s49, s49, 0
	s_add_u32 s50, s50, 0x18000
	s_addc_u32 s51, s51, 0
	s_add_u32 s52, s52, 0x18000
	s_addc_u32 s53, s53, 0
	s_add_u32 s54, s54, 0x18000
	s_addc_u32 s55, s55, 0
	s_add_u32 s56, s56, 0x18000
	s_addc_u32 s57, s57, 0
	s_add_u32 s58, s58, 0x18000
	s_addc_u32 s59, s59, 0
	s_add_u32 s60, s60, 0xc000
	s_addc_u32 s61, s61, 0
	s_add_u32 s62, s62, s83
	s_addc_u32 s63, s63, 0
	s_add_u32 s72, s72, 24
	s_addc_u32 s73, s73, 0
	global_load_dwordx4 v[40:43], v120, s[44:45]
	global_load_dwordx4 v[44:47], v120, s[46:47]
	global_load_dwordx4 v[48:51], v120, s[48:49]
	global_load_dwordx4 v[52:55], v120, s[50:51]
	global_load_dwordx4 v[56:59], v120, s[52:53]
	global_load_dwordx4 v[60:63], v120, s[54:55]
	global_load_dwordx4 v[64:67], v120, s[56:57]
	global_load_dwordx4 v[68:71], v120, s[58:59]
	global_load_dwordx4 v[72:75], v120, s[60:61]
	global_load_dwordx4 v[76:79], v120, s[62:63]
	global_load_dword v128, v121, s[72:73]
	s_add_u32 s44, s44, 0x18000
	s_addc_u32 s45, s45, 0
	s_add_u32 s46, s46, 0x18000
	s_addc_u32 s47, s47, 0
	s_add_u32 s48, s48, 0x18000
	s_addc_u32 s49, s49, 0
	s_add_u32 s50, s50, 0x18000
	s_addc_u32 s51, s51, 0
	s_add_u32 s52, s52, 0x18000
	s_addc_u32 s53, s53, 0
	s_add_u32 s54, s54, 0x18000
	s_addc_u32 s55, s55, 0
	s_add_u32 s56, s56, 0x18000
	s_addc_u32 s57, s57, 0
	s_add_u32 s58, s58, 0x18000
	s_addc_u32 s59, s59, 0
	s_add_u32 s60, s60, 0xc000
	s_addc_u32 s61, s61, 0
	s_add_u32 s62, s62, s83
	s_addc_u32 s63, s63, 0
	s_add_u32 s72, s72, 24
	s_addc_u32 s73, s73, 0
	global_load_dwordx4 v[80:83], v120, s[44:45]
	global_load_dwordx4 v[84:87], v120, s[46:47]
	global_load_dwordx4 v[88:91], v120, s[48:49]
	global_load_dwordx4 v[92:95], v120, s[50:51]
	global_load_dwordx4 v[96:99], v120, s[52:53]
	global_load_dwordx4 v[100:103], v120, s[54:55]
	global_load_dwordx4 v[104:107], v120, s[56:57]
	global_load_dwordx4 v[108:111], v120, s[58:59]
	global_load_dwordx4 v[112:115], v120, s[60:61]
	global_load_dwordx4 v[116:119], v120, s[62:63]
	global_load_dword v129, v121, s[72:73]
	s_add_u32 s44, s44, 0x18000
	s_addc_u32 s45, s45, 0
	s_add_u32 s46, s46, 0x18000
	s_addc_u32 s47, s47, 0
	s_add_u32 s48, s48, 0x18000
	s_addc_u32 s49, s49, 0
	s_add_u32 s50, s50, 0x18000
	s_addc_u32 s51, s51, 0
	s_add_u32 s52, s52, 0x18000
	s_addc_u32 s53, s53, 0
	s_add_u32 s54, s54, 0x18000
	s_addc_u32 s55, s55, 0
	s_add_u32 s56, s56, 0x18000
	s_addc_u32 s57, s57, 0
	s_add_u32 s58, s58, 0x18000
	s_addc_u32 s59, s59, 0
	s_add_u32 s60, s60, 0xc000
	s_addc_u32 s61, s61, 0
	s_add_u32 s62, s62, s83
	s_addc_u32 s63, s63, 0
	s_add_u32 s72, s72, 24
	s_addc_u32 s73, s73, 0
	global_load_dwordx4 v[176:179], v120, s[44:45]
	global_load_dwordx4 v[180:183], v120, s[46:47]
	global_load_dwordx4 v[184:187], v120, s[48:49]
	global_load_dwordx4 v[188:191], v120, s[50:51]
	global_load_dwordx4 v[192:195], v120, s[52:53]
	global_load_dwordx4 v[196:199], v120, s[54:55]
	global_load_dwordx4 v[200:203], v120, s[56:57]
	global_load_dwordx4 v[204:207], v120, s[58:59]
	global_load_dwordx4 v[208:211], v120, s[60:61]
	global_load_dwordx4 v[212:215], v120, s[62:63]
	global_load_dword v133, v121, s[72:73]
	s_add_u32 s44, s44, 0x18000
	s_addc_u32 s45, s45, 0
	s_add_u32 s46, s46, 0x18000
	s_addc_u32 s47, s47, 0
	s_add_u32 s48, s48, 0x18000
	s_addc_u32 s49, s49, 0
	s_add_u32 s50, s50, 0x18000
	s_addc_u32 s51, s51, 0
	s_add_u32 s52, s52, 0x18000
	s_addc_u32 s53, s53, 0
	s_add_u32 s54, s54, 0x18000
	s_addc_u32 s55, s55, 0
	s_add_u32 s56, s56, 0x18000
	s_addc_u32 s57, s57, 0
	s_add_u32 s58, s58, 0x18000
	s_addc_u32 s59, s59, 0
	s_add_u32 s60, s60, 0xc000
	s_addc_u32 s61, s61, 0
	s_add_u32 s62, s62, s83
	s_addc_u32 s63, s63, 0
	s_add_u32 s72, s72, 24
	s_addc_u32 s73, s73, 0
	s_waitcnt lgkmcnt(0)
	s_barrier
	s_mov_b32 s81, 1
.Lg2l_loop:
	s_cmpk_lt_u32 s81, 0xf0
	s_cbranch_scc0 .Lg2l_tail_2
	s_and_b32 s0, s81, 1
	v_lshl_add_u32 v131, s0, 16, v125
	s_waitcnt vmcnt(33)
	ds_write_b128 v131, v[0:3]
	ds_write_b128 v131, v[4:7] offset:6144
	ds_write_b128 v131, v[8:11] offset:12288
	ds_write_b128 v131, v[12:15] offset:18432
	ds_write_b128 v131, v[16:19] offset:24576
	ds_write_b128 v131, v[20:23] offset:30720
	ds_write_b128 v131, v[24:27] offset:36864
	ds_write_b128 v131, v[28:31] offset:43008
	ds_write_b128 v131, v[32:35] offset:49152
	ds_write_b128 v131, v[36:39] offset:55296
	s_and_saveexec_b64 s[8:9], s[6:7]
	s_cbranch_execz .Lg2l_nocd_3
	s_lshl_b32 s0, s0, 2
	v_add_u32_e32 v130, s0, v132
	ds_write_b32 v130, v127

.Lg2l_std_2:
	s_add_i32 s82, s81, 4
	s_cmpk_lt_u32 s82, 0x100
	s_cbranch_scc0 .Lg2l_nold_2
	s_cmp_lt_i32 s82, s80
	s_cbranch_scc1 .Lg2l_rdy_5
	s_add_i32 s0, s82, 16
	s_min_i32 s0, s0, 0x100

.Lg2l_nold_2:
	s_waitcnt lgkmcnt(0)
	s_barrier
	s_add_i32 s81, s81, 1
	s_cmpk_lt_u32 s81, 0x100
	s_cbranch_scc0 .Lg2l_exit
	s_cmpk_lt_u32 s81, 0xf0
	s_cbranch_scc0 .Lg2l_tail_6
	s_and_b32 s0, s81, 1
	v_lshl_add_u32 v131, s0, 16, v125
	s_waitcnt vmcnt(33)
	ds_write_b128 v131, v[40:43]
	ds_write_b128 v131, v[44:47] offset:6144
	ds_write_b128 v131, v[48:51] offset:12288
	ds_write_b128 v131, v[52:55] offset:18432
	ds_write_b128 v131, v[56:59] offset:24576
	ds_write_b128 v131, v[60:63] offset:30720
	ds_write_b128 v131, v[64:67] offset:36864
	ds_write_b128 v131, v[68:71] offset:43008
	ds_write_b128 v131, v[72:75] offset:49152
	ds_write_b128 v131, v[76:79] offset:55296
	s_and_saveexec_b64 s[8:9], s[6:7]
	s_cbranch_execz .Lg2l_nocd_7
	s_lshl_b32 s0, s0, 2
	v_add_u32_e32 v130, s0, v132
	ds_write_b32 v130, v128

.Lg2l_nold_6:
	s_waitcnt lgkmcnt(0)
	s_barrier
	s_add_i32 s81, s81, 1
	s_cmpk_lt_u32 s81, 0x100
	s_cbranch_scc0 .Lg2l_exit
	s_cmpk_lt_u32 s81, 0xf0
	s_cbranch_scc0 .Lg2l_tail_10
	s_and_b32 s0, s81, 1
	v_lshl_add_u32 v131, s0, 16, v125
	s_waitcnt vmcnt(33)
	ds_write_b128 v131, v[80:83]
	ds_write_b128 v131, v[84:87] offset:6144
	ds_write_b128 v131, v[88:91] offset:12288
	ds_write_b128 v131, v[92:95] offset:18432
	ds_write_b128 v131, v[96:99] offset:24576
	ds_write_b128 v131, v[100:103] offset:30720
	ds_write_b128 v131, v[104:107] offset:36864
	ds_write_b128 v131, v[108:111] offset:43008
	ds_write_b128 v131, v[112:115] offset:49152
	ds_write_b128 v131, v[116:119] offset:55296
	s_and_saveexec_b64 s[8:9], s[6:7]
	s_cbranch_execz .Lg2l_nocd_11
	s_lshl_b32 s0, s0, 2
	v_add_u32_e32 v130, s0, v132
	ds_write_b32 v130, v129

.Lg2l_nold_10:
	s_waitcnt lgkmcnt(0)
	s_barrier
	s_add_i32 s81, s81, 1
	s_cmpk_lt_u32 s81, 0x100
	s_cbranch_scc0 .Lg2l_exit
	s_cmpk_lt_u32 s81, 0xf0
	s_cbranch_scc0 .Lg2l_tail_14
	s_and_b32 s0, s81, 1
	v_lshl_add_u32 v131, s0, 16, v125
	s_waitcnt vmcnt(33)
	ds_write_b128 v131, v[176:179]
	ds_write_b128 v131, v[180:183] offset:6144
	ds_write_b128 v131, v[184:187] offset:12288
	ds_write_b128 v131, v[188:191] offset:18432
	ds_write_b128 v131, v[192:195] offset:24576
	ds_write_b128 v131, v[196:199] offset:30720
	ds_write_b128 v131, v[200:203] offset:36864
	ds_write_b128 v131, v[204:207] offset:43008
	ds_write_b128 v131, v[208:211] offset:49152
	ds_write_b128 v131, v[212:215] offset:55296
	s_and_saveexec_b64 s[8:9], s[6:7]
	s_cbranch_execz .Lg2l_nocd_15
	s_lshl_b32 s0, s0, 2
	v_add_u32_e32 v130, s0, v132
	ds_write_b32 v130, v133

.Lg2l_tail_14:
	s_and_b32 s0, s81, 1
	v_lshl_add_u32 v131, s0, 16, v125
	s_waitcnt vmcnt(0)
	ds_write_b128 v131, v[176:179]
	ds_write_b128 v131, v[180:183] offset:6144
	ds_write_b128 v131, v[184:187] offset:12288
	ds_write_b128 v131, v[188:191] offset:18432
	ds_write_b128 v131, v[192:195] offset:24576
	ds_write_b128 v131, v[196:199] offset:30720
	ds_write_b128 v131, v[200:203] offset:36864
	ds_write_b128 v131, v[204:207] offset:43008
	ds_write_b128 v131, v[208:211] offset:49152
	ds_write_b128 v131, v[212:215] offset:55296
	s_and_saveexec_b64 s[8:9], s[6:7]
	s_cbranch_execz .Lg2l_nocd_16
	s_lshl_b32 s0, s0, 2
	v_add_u32_e32 v130, s0, v132
	ds_write_b32 v130, v133

.Lg2l_rdy_17:
	global_load_dwordx4 v[176:179], v120, s[44:45]
	global_load_dwordx4 v[180:183], v120, s[46:47]
	global_load_dwordx4 v[184:187], v120, s[48:49]
	global_load_dwordx4 v[188:191], v120, s[50:51]
	global_load_dwordx4 v[192:195], v120, s[52:53]
	global_load_dwordx4 v[196:199], v120, s[54:55]
	global_load_dwordx4 v[200:203], v120, s[56:57]
	global_load_dwordx4 v[204:207], v120, s[58:59]
	global_load_dwordx4 v[208:211], v120, s[60:61]
	global_load_dwordx4 v[212:215], v120, s[62:63]
	global_load_dword v133, v121, s[72:73]
	s_add_u32 s44, s44, 0x18000
	s_addc_u32 s45, s45, 0
	s_add_u32 s46, s46, 0x18000
	s_addc_u32 s47, s47, 0
	s_add_u32 s48, s48, 0x18000
	s_addc_u32 s49, s49, 0
	s_add_u32 s50, s50, 0x18000
	s_addc_u32 s51, s51, 0
	s_add_u32 s52, s52, 0x18000
	s_addc_u32 s53, s53, 0
	s_add_u32 s54, s54, 0x18000
	s_addc_u32 s55, s55, 0
	s_add_u32 s56, s56, 0x18000
	s_addc_u32 s57, s57, 0
	s_add_u32 s58, s58, 0x18000
	s_addc_u32 s59, s59, 0
	s_add_u32 s60, s60, 0xc000
	s_addc_u32 s61, s61, 0
	s_add_u32 s62, s62, s83
	s_addc_u32 s63, s63, 0
	s_add_u32 s72, s72, 24
	s_addc_u32 s73, s73, 0
